# group barrier uses one flag word per member (plain store + L1-bypassing loads served by the shared XCD L2) instead of a device-scope atomic counter
# speedup vs baseline: 1.0461x; 1.0144x over previous
.LBB0_152:
	s_waitcnt vmcnt(0) lgkmcnt(0)
	v_mov_b32_e32 v1, 0
	v_mov_b32_e32 v3, 1
	v_readlane_b32 s20, v162, 62
	v_readlane_b32 s21, v164, 0
	v_readlane_b32 s22, v162, 63
	s_cmp_eq_u32 s20, 1
	s_cbranch_scc0 .Lxb21_glob
	s_and_b32 s4, s21, 15
	s_lshl_b32 s4, s4, 8
	s_bfe_u32 s5, s21, 0x20004
	s_lshl_b32 s5, s5, 5
	s_add_u32 s4, s4, s5
	s_add_u32 s4, s4, 0x480
	s_add_u32 s4, s84, s4
	s_addc_u32 s5, s85, 0
	s_add_u32 s22, s22, 1
	s_nop 1
	v_writelane_b32 v162, s22, 63
	s_lshr_b32 s21, s21, 6
	s_lshl_b32 s21, s21, 2
	v_mov_b32_e32 v5, s21
	v_mov_b32_e32 v6, s22
	global_store_dword v5, v6, s[4:5]
	s_waitcnt vmcnt(0)
	s_mov_b32 s20, 0
.Lxb21_gspin:
	global_load_dwordx4 v[8:11], v1, s[4:5] sc1
	global_load_dwordx4 v[12:15], v1, s[4:5] offset:16 sc1
	s_waitcnt vmcnt(0)
	v_min_u32_e32 v8, v8, v9
	v_min_u32_e32 v10, v10, v11
	v_min_u32_e32 v12, v12, v13
	v_min_u32_e32 v14, v14, v15
	v_min_u32_e32 v8, v8, v10
	v_min_u32_e32 v12, v12, v14
	s_nop 0
	v_min_u32_e32 v8, v8, v12
	s_nop 0
	v_readfirstlane_b32 s21, v8
	s_cmp_ge_u32 s21, s22
	s_cbranch_scc1 .Lxb21_done
	s_sleep 1
	s_add_u32 s20, s20, 1
	s_cmp_lt_u32 s20, 0x10000
	s_cbranch_scc1 .Lxb21_gspin
	s_branch .Lxb21_done

.Lxb0_ninv:
	s_barrier
	s_and_saveexec_b64 s[2:3], s[4:5]
	s_cbranch_execz .LBB0_246
	s_waitcnt vmcnt(0) lgkmcnt(0)
	v_readlane_b32 s20, v162, 62
	v_readlane_b32 s21, v164, 0
	v_readlane_b32 s22, v162, 63
	s_cmp_eq_u32 s20, 1
	s_cbranch_scc0 .Lxb0_glob
	s_and_b32 s4, s21, 15
	s_lshl_b32 s4, s4, 8
	s_bfe_u32 s5, s21, 0x20004
	s_lshl_b32 s5, s5, 5
	s_add_u32 s4, s4, s5
	s_add_u32 s4, s4, 0x480
	s_add_u32 s4, s84, s4
	s_addc_u32 s5, s85, 0
	s_add_u32 s22, s22, 1
	s_nop 1
	v_writelane_b32 v162, s22, 63
	s_lshr_b32 s21, s21, 6
	s_lshl_b32 s21, s21, 2
	v_mov_b32_e32 v5, s21
	v_mov_b32_e32 v6, s22
	global_store_dword v5, v6, s[4:5]
	s_waitcnt vmcnt(0)
	s_mov_b32 s20, 0
.Lxb0_gspin:
	global_load_dwordx4 v[8:11], v117, s[4:5] sc1
	global_load_dwordx4 v[12:15], v117, s[4:5] offset:16 sc1
	s_waitcnt vmcnt(0)
	v_min_u32_e32 v8, v8, v9
	v_min_u32_e32 v10, v10, v11
	v_min_u32_e32 v12, v12, v13
	v_min_u32_e32 v14, v14, v15
	v_min_u32_e32 v8, v8, v10
	v_min_u32_e32 v12, v12, v14
	s_nop 0
	v_min_u32_e32 v8, v8, v12
	s_nop 0
	v_readfirstlane_b32 s21, v8
	s_cmp_ge_u32 s21, s22
	s_cbranch_scc1 .Lxb0_done
	s_sleep 1
	s_add_u32 s20, s20, 1
	s_cmp_lt_u32 s20, 0x10000
	s_cbranch_scc1 .Lxb0_gspin
	s_branch .Lxb0_done

.LBB0_1123:
	s_waitcnt vmcnt(0) lgkmcnt(0)
	v_readlane_b32 s20, v162, 62
	v_readlane_b32 s21, v164, 0
	v_readlane_b32 s22, v162, 63
	s_cmp_eq_u32 s20, 1
	s_cbranch_scc0 .Lxb11_glob
	s_and_b32 s4, s21, 15
	s_lshl_b32 s4, s4, 8
	s_bfe_u32 s5, s21, 0x20004
	s_lshl_b32 s5, s5, 5
	s_add_u32 s4, s4, s5
	s_add_u32 s4, s4, 0x480
	s_add_u32 s4, s84, s4
	s_addc_u32 s5, s85, 0
	s_add_u32 s22, s22, 1
	s_nop 1
	v_writelane_b32 v162, s22, 63
	s_lshr_b32 s21, s21, 6
	s_lshl_b32 s21, s21, 2
	v_mov_b32_e32 v5, s21
	v_mov_b32_e32 v6, s22
	global_store_dword v5, v6, s[4:5]
	s_waitcnt vmcnt(0)
	s_mov_b32 s20, 0
